# attention: staggered waves 4-7; dropped the m=0 softmax fast path (always subtract the running max, as the baseline does)
# baseline (speedup 1.0000x reference)
; #define LAS __attribute__((address_space(3)))
; __device__ __forceinline__ float fexp2(float x) { return __builtin_amdgcn_exp2f(x); }
; template <int MODE>
; __device__ __forceinline__ void attn_pv(const LAS unsigned char* vb_, f32x16 (&st)[2], f32x16 (&ot)[2], float& mrun, float& lsum, const int ql, const int hf, const int lane) {
;     if (MODE != 1) {
;     float mx = max3f(st[0][0], st[1][0], st[0][1]), my = max3f(st[1][1], st[0][2], st[1][2]);
; #pragma unroll
;     for (int i = 3; i < 15; i += 2) { mx = max3f(mx, st[0][i], st[1][i]); my = max3f(my, st[0][i + 1], st[1][i + 1]); }
;     mx = max3f(mx, st[0][15], st[1][15]); mx = max3f(mx, my, my);
;     if (__builtin_amdgcn_ballot_w64(mx > mrun + 8.0f) != 0ull) {
;         mx = fmaxf(mx, shx32(mx, lane));
;         const float mnew = (mx > mrun + 8.0f) ? mx : mrun;
;         const float alpha = fexp2(mrun - mnew);
;         mrun = mnew; lsum *= alpha;
; #pragma unroll
;         for (int i = 0; i < 16; ++i) { ot[0][i] *= alpha; ot[1][i] *= alpha; }
;     }
;     float ps = 0.f;
; #pragma unroll
;     for (int kb = 0; kb < 2; ++kb)
; #pragma unroll
;         for (int i = 0; i < 16; ++i) { const float p = fexp2(st[kb][i] - mrun); st[kb][i] = p; ps += p; }
;     lsum += ps;
;     } else lsum += st[0][0];
; #pragma unroll
;     for (int kb = 0; kb < 2; ++kb)
; #pragma unroll
;         for (int sI = 0; sI < 2; ++sI) {
;             u32x4 pw = {pk_bf16(st[kb][8 * sI + 0], st[kb][8 * sI + 1]), pk_bf16(st[kb][8 * sI + 2], st[kb][8 * sI + 3]),
;                         pk_bf16(st[kb][8 * sI + 4], st[kb][8 * sI + 5]), pk_bf16(st[kb][8 * sI + 6], st[kb][8 * sI + 7])};
;             const bf16x8 pf = __builtin_bit_cast(bf16x8, pw);
; #pragma unroll
;             for (int db = 0; db < 2; ++db) {
;                 const LAS unsigned char* vp = vb_ + (db * 32 + ql) * VROW + (kb * 32 + 16 * sI + 4 * hf) * 2;
;                 const u32x2 v0 = *(const LAS u32x2*)vp, v1 = *(const LAS u32x2*)(vp + 16);
;                 u32x4 vw = {v0[0], v0[1], v1[0], v1[1]};
;                 ot[db] = att_mma<MODE>(__builtin_bit_cast(bf16x8, vw), pf, ot[db]);
;             }
;         }
; }
; template <int MODE>
; __device__ __forceinline__ void attn_phase(const Args& a, bool do_ctx, LAS unsigned char* lds, const int wid_s) {
;     ...
;             if (t + 2 < nkt) ATT_WRITEK(kK, kR, 0);
;             ATT_WRITEV(vV, 1);
.LBB0_437:
	global_load_dwordx4 v[128:131], v150, s[84:85] offset:128
	s_cmp_lg_u32 s96, 0
	s_cbranch_scc1 .LattB_e
	ds_read_b128 v[64:67], v165 offset:13312
	ds_read_b128 v[168:171], v165 offset:13344
	ds_read_b128 v[68:71], v165 offset:19968
	ds_read_b128 v[172:175], v165 offset:20000
	ds_read_b128 v[176:179], v165 offset:13376
	ds_read_b128 v[180:183], v165 offset:13408
	ds_read_b128 v[184:187], v165 offset:20032
	ds_read_b128 v[188:191], v165 offset:20064
	ds_read_b128 v[206:209], v240 offset:31232
	ds_read_b128 v[210:213], v240 offset:26624
	ds_read_b128 v[214:217], v240 offset:31264
	ds_read_b128 v[218:221], v240 offset:26656
	ds_read_b128 v[222:225], v240 offset:31296
	ds_read_b128 v[226:229], v240 offset:26688
	ds_read_b128 v[236:239], v240 offset:26720
	v_max3_f32 v156, v48, v32, v49
	v_max3_f32 v157, v33, v50, v34
	v_max3_f32 v156, v156, v51, v35
	v_max3_f32 v157, v157, v52, v36
	v_max3_f32 v156, v156, v53, v37
	v_max3_f32 v157, v157, v54, v38
	v_max3_f32 v156, v156, v55, v39
	v_max3_f32 v157, v157, v56, v40
	v_max3_f32 v156, v156, v57, v41
	v_max3_f32 v157, v157, v58, v42
	v_max3_f32 v156, v156, v59, v43
	v_max3_f32 v157, v157, v60, v44
	v_max3_f32 v156, v156, v61, v45
	v_max3_f32 v157, v157, v62, v46
	v_max3_f32 v156, v156, v63, v47
	v_max3_f32 v157, v156, v157, v157
	v_add_f32_e32 v156, 0x41000000, v143
	v_cmp_gt_f32_e32 vcc, v157, v156
	s_cbranch_vccnz .Latt_e_nors_resc
.Latt_e_nors:
	v_sub_f32_e32 v48, v48, v143
	v_sub_f32_e32 v49, v49, v143
	v_sub_f32_e32 v50, v50, v143
	v_sub_f32_e32 v51, v51, v143
	v_sub_f32_e32 v52, v52, v143
	v_sub_f32_e32 v53, v53, v143
	v_sub_f32_e32 v54, v54, v143
	v_sub_f32_e32 v55, v55, v143
	v_exp_f32_e32 v48, v48
	v_exp_f32_e32 v49, v49
	v_exp_f32_e32 v50, v50
	v_exp_f32_e32 v51, v51
	v_exp_f32_e32 v52, v52
	v_exp_f32_e32 v53, v53
	v_exp_f32_e32 v54, v54
	v_exp_f32_e32 v55, v55
	s_waitcnt lgkmcnt(11)
	v_mfma_f32_32x32x16_bf16 v[80:95], v[64:67], v[112:115], 0
	v_cvt_pk_bf16_f32 v152, v48, v49
	v_cvt_pk_bf16_f32 v153, v50, v51
	v_cvt_pk_bf16_f32 v154, v52, v53
	v_cvt_pk_bf16_f32 v155, v54, v55
	v_mfma_f32_32x32x16_bf16 v[64:79], v[68:71], v[112:115], 0
	v_pk_add_f32 v[230:231], v[48:49], v[50:51]
	v_pk_add_f32 v[230:231], v[230:231], v[52:53]
	v_pk_add_f32 v[230:231], v[230:231], v[54:55]
	v_mfma_f32_32x32x16_bf16 v[80:95], v[168:171], v[96:99], v[80:95]
	v_sub_f32_e32 v56, v56, v143
	v_sub_f32_e32 v57, v57, v143
	v_sub_f32_e32 v58, v58, v143
	v_sub_f32_e32 v59, v59, v143
	v_sub_f32_e32 v60, v60, v143
	v_sub_f32_e32 v61, v61, v143
	v_sub_f32_e32 v62, v62, v143
	v_sub_f32_e32 v63, v63, v143
	v_mfma_f32_32x32x16_bf16 v[64:79], v[172:175], v[96:99], v[64:79]
	ds_read_b128 v[168:171], v165 offset:13440
	ds_read_b128 v[172:175], v165 offset:13472
	ds_read_b128 v[192:195], v165 offset:20096
	ds_read_b128 v[196:199], v165 offset:20128
	v_exp_f32_e32 v56, v56
	v_exp_f32_e32 v57, v57
	v_exp_f32_e32 v58, v58
	v_exp_f32_e32 v59, v59
	s_waitcnt lgkmcnt(11)
	v_mfma_f32_32x32x16_bf16 v[80:95], v[176:179], v[100:103], v[80:95]
	ds_read_b128 a[0:3], v240 offset:31328
	v_exp_f32_e32 v60, v60
	v_exp_f32_e32 v61, v61
	v_exp_f32_e32 v62, v62
	v_exp_f32_e32 v63, v63
	v_mfma_f32_32x32x16_bf16 v[64:79], v[184:187], v[100:103], v[64:79]
	v_mfma_f32_32x32x16_bf16 v[80:95], v[180:183], v[104:107], v[80:95]
	v_cvt_pk_bf16_f32 v48, v56, v57
	v_cvt_pk_bf16_f32 v49, v58, v59
	v_cvt_pk_bf16_f32 v50, v60, v61
	v_cvt_pk_bf16_f32 v51, v62, v63
	v_mfma_f32_32x32x16_bf16 v[64:79], v[188:191], v[104:107], v[64:79]
	s_waitcnt lgkmcnt(10)
	v_mfma_f32_32x32x16_bf16 v[16:31], v[206:209], v[152:155], v[16:31]
	v_pk_add_f32 v[230:231], v[230:231], v[56:57]
	v_pk_add_f32 v[230:231], v[230:231], v[58:59]
	v_pk_add_f32 v[230:231], v[230:231], v[60:61]
	v_pk_add_f32 v[230:231], v[230:231], v[62:63]
	v_mfma_f32_32x32x16_bf16 v[0:15], v[210:213], v[152:155], v[0:15]
	v_sub_f32_e32 v32, v32, v143
	v_sub_f32_e32 v33, v33, v143
	v_sub_f32_e32 v34, v34, v143
	v_sub_f32_e32 v35, v35, v143
	v_sub_f32_e32 v36, v36, v143
	v_sub_f32_e32 v37, v37, v143
	v_sub_f32_e32 v38, v38, v143
	v_sub_f32_e32 v39, v39, v143
	s_waitcnt lgkmcnt(1)
	v_mfma_f32_32x32x16_bf16 v[80:95], v[168:171], v[108:111], v[80:95]
	v_exp_f32_e32 v32, v32
	v_exp_f32_e32 v33, v33
	v_exp_f32_e32 v34, v34
	v_exp_f32_e32 v35, v35
	v_mfma_f32_32x32x16_bf16 v[16:31], v[214:217], v[48:51], v[16:31]
	v_exp_f32_e32 v36, v36
	v_exp_f32_e32 v37, v37
	v_exp_f32_e32 v38, v38
	v_exp_f32_e32 v39, v39
	v_mfma_f32_32x32x16_bf16 v[0:15], v[218:221], v[48:51], v[0:15]
	v_cvt_pk_bf16_f32 v152, v32, v33
	v_cvt_pk_bf16_f32 v153, v34, v35
	v_cvt_pk_bf16_f32 v154, v36, v37
	v_cvt_pk_bf16_f32 v155, v38, v39
	v_mfma_f32_32x32x16_bf16 v[64:79], v[192:195], v[108:111], v[64:79]
	v_pk_add_f32 v[230:231], v[230:231], v[32:33]
	v_pk_add_f32 v[230:231], v[230:231], v[34:35]
	v_pk_add_f32 v[230:231], v[230:231], v[36:37]
	v_pk_add_f32 v[230:231], v[230:231], v[38:39]
	v_mfma_f32_32x32x16_bf16 v[80:95], v[172:175], v[116:119], v[80:95]
	v_sub_f32_e32 v40, v40, v143
	v_sub_f32_e32 v41, v41, v143
	v_sub_f32_e32 v42, v42, v143
	v_sub_f32_e32 v43, v43, v143
	v_sub_f32_e32 v44, v44, v143
	v_sub_f32_e32 v45, v45, v143
	v_sub_f32_e32 v46, v46, v143
	v_sub_f32_e32 v47, v47, v143
	v_mfma_f32_32x32x16_bf16 v[64:79], v[196:199], v[116:119], v[64:79]
	s_andn2_b64 vcc, exec, s[10:11]
	s_cbranch_vccnz .Latt_wskip_e1
	s_waitcnt vmcnt(2)
	ds_write_b128 v162, v[120:123]
	s_and_saveexec_b64 s[2:3], s[6:7]
	s_cbranch_execz .Latt_wk_e1
	s_waitcnt vmcnt(1)
	ds_write_b128 v164, v[124:127] offset:128

; #define LAS __attribute__((address_space(3)))
; __device__ __forceinline__ unsigned pk_bf16(float lo, float hi) { unsigned r; asm("v_cvt_pk_bf16_f32 %0, %1, %2" : "=v"(r) : "v"(lo), "v"(hi)); return r; }
; __device__ __forceinline__ float fexp2(float x) { return __builtin_amdgcn_exp2f(x); }
; #define ATT_LOADK(rk, rr, kt_) do { if (MODE == 3 && (kt_) > 1) break; rk = *(const u32x4*)(gkn + (size_t)(kt_) * 64 * 512); rr = *(const u32x4*)(gkr + (size_t)(kt_) * 64 * 32); } while (0)
; #define ATT_WRITEK(rk, rr, buf) do { LAS unsigned char* nb_ = lds + (buf) * KBUF; *(LAS u32x4*)(nb_ + skn) = rk; if (tid < 256) *(LAS u32x4*)(nb_ + skr) = rr; } while (0)
; template <int MODE>
; __device__ __forceinline__ void attn_pv(const LAS unsigned char* vb_, f32x16 (&st)[2], f32x16 (&ot)[2], float& mrun, float& lsum, const int ql, const int hf, const int lane) {
;     ...
;     float ps = 0.f;
; #pragma unroll
;     for (int kb = 0; kb < 2; ++kb)
; #pragma unroll
;         for (int i = 0; i < 16; ++i) { const float p = fexp2(st[kb][i] - mrun); st[kb][i] = p; ps += p; }
;     lsum += ps;
;     } else lsum += st[0][0];
; #pragma unroll
;     for (int kb = 0; kb < 2; ++kb)
; #pragma unroll
;         for (int sI = 0; sI < 2; ++sI) {
;             u32x4 pw = {pk_bf16(st[kb][8 * sI + 0], st[kb][8 * sI + 1]), pk_bf16(st[kb][8 * sI + 2], st[kb][8 * sI + 3]),
;                         pk_bf16(st[kb][8 * sI + 4], st[kb][8 * sI + 5]), pk_bf16(st[kb][8 * sI + 6], st[kb][8 * sI + 7])};
;             const bf16x8 pf = __builtin_bit_cast(bf16x8, pw);
; #pragma unroll
;             for (int db = 0; db < 2; ++db) {
;                 const LAS unsigned char* vp = vb_ + (db * 32 + ql) * VROW + (kb * 32 + 16 * sI + 4 * hf) * 2;
;                 const u32x2 v0 = *(const LAS u32x2*)vp, v1 = *(const LAS u32x2*)(vp + 16);
;                 u32x4 vw = {v0[0], v0[1], v1[0], v1[1]};
;                 ot[db] = att_mma<MODE>(__builtin_bit_cast(bf16x8, vw), pf, ot[db]);
;             }
;         }
; }
; template <int MODE>
; __device__ __forceinline__ void attn_phase(const Args& a, bool do_ctx, LAS unsigned char* lds, const int wid_s) {
;     ...
;             if (t + 2 < nkt) ATT_WRITEK(kK, kR, 0);
;             ATT_WRITEV(vV, 1);
;             __syncthreads();
;             if (t + 3 < nkt) ATT_LOADK(kK, kR, t + 3);
.Latt_wskip_e1:
	s_waitcnt vmcnt(0)
	ds_write2_b64 v251, v[128:129], v[130:131] offset1:2
	v_exp_f32_e32 v40, v40
	v_exp_f32_e32 v41, v41
	v_exp_f32_e32 v42, v42
	v_exp_f32_e32 v43, v43
	v_mfma_f32_32x32x16_bf16 v[16:31], v[222:225], v[152:155], v[16:31]
	v_exp_f32_e32 v44, v44
	v_exp_f32_e32 v45, v45
	v_exp_f32_e32 v46, v46
	v_exp_f32_e32 v47, v47
	v_mfma_f32_32x32x16_bf16 v[0:15], v[226:229], v[152:155], v[0:15]
	v_cvt_pk_bf16_f32 v48, v40, v41
	v_cvt_pk_bf16_f32 v49, v42, v43
	v_cvt_pk_bf16_f32 v50, v44, v45
	v_cvt_pk_bf16_f32 v51, v46, v47
	v_pk_add_f32 v[230:231], v[230:231], v[40:41]
	v_pk_add_f32 v[230:231], v[230:231], v[42:43]
	v_pk_add_f32 v[230:231], v[230:231], v[44:45]
	v_pk_add_f32 v[230:231], v[230:231], v[46:47]
	v_add_f32_e32 v230, v230, v231
	v_add_f32_e32 v167, v167, v230
	s_waitcnt lgkmcnt(0)
	v_mfma_f32_32x32x16_bf16 v[0:15], v[236:239], v[48:51], v[0:15]
	v_mfma_f32_32x32x16_bf16 v[16:31], a[0:3], v[48:51], v[16:31]
	s_not_b64 s[8:9], s[10:11]
	s_cmp_lt_u32 s12, s25
	s_cselect_b64 s[10:11], -1, 0
	s_cmp_ge_u32 s12, s25
	s_waitcnt lgkmcnt(0)
	s_barrier

; #define LAS __attribute__((address_space(3)))
; template <int MODE>
; __device__ __forceinline__ void attn_pv(const LAS unsigned char* vb_, f32x16 (&st)[2], f32x16 (&ot)[2], float& mrun, float& lsum, const int ql, const int hf, const int lane) {
;     if (MODE != 1) {
;     float mx = max3f(st[0][0], st[1][0], st[0][1]), my = max3f(st[1][1], st[0][2], st[1][2]);
; #pragma unroll
;     for (int i = 3; i < 15; i += 2) { mx = max3f(mx, st[0][i], st[1][i]); my = max3f(my, st[0][i + 1], st[1][i + 1]); }
;     mx = max3f(mx, st[0][15], st[1][15]); mx = max3f(mx, my, my);
;     if (__builtin_amdgcn_ballot_w64(mx > mrun + 8.0f) != 0ull) {
;         mx = fmaxf(mx, shx32(mx, lane));
;         const float mnew = (mx > mrun + 8.0f) ? mx : mrun;
;         const float alpha = fexp2(mrun - mnew);
;         mrun = mnew; lsum *= alpha;
; #pragma unroll
;         for (int i = 0; i < 16; ++i) { ot[0][i] *= alpha; ot[1][i] *= alpha; }
;     }
;     float ps = 0.f;
; #pragma unroll
;     for (int kb = 0; kb < 2; ++kb)
; #pragma unroll
;         for (int i = 0; i < 16; ++i) { const float p = fexp2(st[kb][i] - mrun); st[kb][i] = p; ps += p; }
;     lsum += ps;
;     } else lsum += st[0][0];
; #pragma unroll
;     for (int kb = 0; kb < 2; ++kb)
; #pragma unroll
;         for (int sI = 0; sI < 2; ++sI) {
;             u32x4 pw = {pk_bf16(st[kb][8 * sI + 0], st[kb][8 * sI + 1]), pk_bf16(st[kb][8 * sI + 2], st[kb][8 * sI + 3]),
;                         pk_bf16(st[kb][8 * sI + 4], st[kb][8 * sI + 5]), pk_bf16(st[kb][8 * sI + 6], st[kb][8 * sI + 7])};
;             const bf16x8 pf = __builtin_bit_cast(bf16x8, pw);
; #pragma unroll
;             for (int db = 0; db < 2; ++db) {
;                 const LAS unsigned char* vp = vb_ + (db * 32 + ql) * VROW + (kb * 32 + 16 * sI + 4 * hf) * 2;
;                 const u32x2 v0 = *(const LAS u32x2*)vp, v1 = *(const LAS u32x2*)(vp + 16);
;                 u32x4 vw = {v0[0], v0[1], v1[0], v1[1]};
; template <int MODE>
; __device__ __forceinline__ void attn_phase(const Args& a, bool do_ctx, LAS unsigned char* lds, const int wid_s) {
;     ...
;             if (t + 3 < nkt) ATT_LOADK(kK, kR, t + 3);
;             if (t + 2 < nkt) ATT_LOADV(vV, t + 2);
;             if (t + 2 < nkt) attn_qk<MODE>(lds, qf, sa, ql, hf);
;             __builtin_amdgcn_sched_barrier(0);
;             attn_pv<MODE>(ldsv + VBUF, sb, ot, mrun, lsum, ql, hf, lane);
.Latt_o_noK:
	s_and_b64 vcc, exec, s[8:9]
	s_cbranch_vccnz .Latt_o_tail
	global_load_dwordx4 v[128:131], v150, s[84:85] offset:256
	s_cmp_lg_u32 s96, 0
	s_cbranch_scc1 .LattB_o
	ds_read_b128 v[32:35], v165
	ds_read_b128 v[152:155], v165 offset:32
	ds_read_b128 v[36:39], v165 offset:6656
	ds_read_b128 v[206:209], v165 offset:6688
	ds_read_b128 v[210:213], v165 offset:64
	ds_read_b128 v[214:217], v165 offset:96
	ds_read_b128 v[218:221], v165 offset:6720
	ds_read_b128 v[222:225], v165 offset:6752
	ds_read_b128 v[176:179], v240 offset:35840
	ds_read_b128 v[180:183], v240 offset:40448
	ds_read_b128 v[184:187], v240 offset:35872
	ds_read_b128 v[188:191], v240 offset:40480
	ds_read_b128 v[192:195], v240 offset:35904
	ds_read_b128 v[196:199], v240 offset:40512
	ds_read_b128 v[172:175], v240 offset:35936
	v_max3_f32 v156, v80, v64, v81
	v_max3_f32 v157, v65, v82, v66
	v_max3_f32 v156, v156, v83, v67
	v_max3_f32 v157, v157, v84, v68
	v_max3_f32 v156, v156, v85, v69
	v_max3_f32 v157, v157, v86, v70
	v_max3_f32 v156, v156, v87, v71
	v_max3_f32 v157, v157, v88, v72
	v_max3_f32 v156, v156, v89, v73
	v_max3_f32 v157, v157, v90, v74
	v_max3_f32 v156, v156, v91, v75
	v_max3_f32 v157, v157, v92, v76
	v_max3_f32 v156, v156, v93, v77
	v_max3_f32 v157, v157, v94, v78
	v_max3_f32 v156, v156, v95, v79
	v_max3_f32 v157, v156, v157, v157
	v_add_f32_e32 v156, 0x41000000, v143
	v_cmp_gt_f32_e32 vcc, v157, v156
	s_cbranch_vccnz .Latt_o_nors_resc
.Latt_o_nors:
	v_sub_f32_e32 v80, v80, v143
	v_sub_f32_e32 v81, v81, v143
	v_sub_f32_e32 v82, v82, v143
	v_sub_f32_e32 v83, v83, v143
	v_sub_f32_e32 v84, v84, v143
	v_sub_f32_e32 v85, v85, v143
	v_sub_f32_e32 v86, v86, v143
	v_sub_f32_e32 v87, v87, v143
	v_exp_f32_e32 v80, v80
	v_exp_f32_e32 v81, v81
	v_exp_f32_e32 v82, v82
	v_exp_f32_e32 v83, v83
	v_exp_f32_e32 v84, v84
	v_exp_f32_e32 v85, v85
	v_exp_f32_e32 v86, v86
	v_exp_f32_e32 v87, v87
	s_waitcnt lgkmcnt(11)
	v_mfma_f32_32x32x16_bf16 v[48:63], v[32:35], v[112:115], 0
	v_cvt_pk_bf16_f32 v168, v80, v81
	v_cvt_pk_bf16_f32 v169, v82, v83
	v_cvt_pk_bf16_f32 v170, v84, v85
	v_cvt_pk_bf16_f32 v171, v86, v87
	v_mfma_f32_32x32x16_bf16 v[32:47], v[36:39], v[112:115], 0
	v_pk_add_f32 v[230:231], v[80:81], v[82:83]
	v_pk_add_f32 v[230:231], v[230:231], v[84:85]
	v_pk_add_f32 v[230:231], v[230:231], v[86:87]
	v_mfma_f32_32x32x16_bf16 v[48:63], v[152:155], v[96:99], v[48:63]
	v_sub_f32_e32 v88, v88, v143
	v_sub_f32_e32 v89, v89, v143
	v_sub_f32_e32 v90, v90, v143
	v_sub_f32_e32 v91, v91, v143
	v_sub_f32_e32 v92, v92, v143
	v_sub_f32_e32 v93, v93, v143
	v_sub_f32_e32 v94, v94, v143
	v_sub_f32_e32 v95, v95, v143
	v_mfma_f32_32x32x16_bf16 v[32:47], v[206:209], v[96:99], v[32:47]
	ds_read_b128 v[152:155], v165 offset:128
	ds_read_b128 v[206:209], v165 offset:160
	ds_read_b128 v[226:229], v165 offset:6784
	ds_read_b128 v[236:239], v165 offset:6816
	v_exp_f32_e32 v88, v88
	v_exp_f32_e32 v89, v89
	v_exp_f32_e32 v90, v90
	v_exp_f32_e32 v91, v91
	s_waitcnt lgkmcnt(11)
	v_mfma_f32_32x32x16_bf16 v[48:63], v[210:213], v[100:103], v[48:63]
	ds_read_b128 a[0:3], v240 offset:40544
	v_exp_f32_e32 v92, v92
	v_exp_f32_e32 v93, v93
	v_exp_f32_e32 v94, v94
	v_exp_f32_e32 v95, v95
	v_mfma_f32_32x32x16_bf16 v[32:47], v[218:221], v[100:103], v[32:47]
	v_mfma_f32_32x32x16_bf16 v[48:63], v[214:217], v[104:107], v[48:63]
	v_cvt_pk_bf16_f32 v80, v88, v89
	v_cvt_pk_bf16_f32 v81, v90, v91
	v_cvt_pk_bf16_f32 v82, v92, v93
	v_cvt_pk_bf16_f32 v83, v94, v95
	v_mfma_f32_32x32x16_bf16 v[32:47], v[222:225], v[104:107], v[32:47]
	s_waitcnt lgkmcnt(10)
	v_mfma_f32_32x32x16_bf16 v[0:15], v[176:179], v[168:171], v[0:15]
	v_pk_add_f32 v[230:231], v[230:231], v[88:89]
	v_pk_add_f32 v[230:231], v[230:231], v[90:91]
	v_pk_add_f32 v[230:231], v[230:231], v[92:93]
	v_pk_add_f32 v[230:231], v[230:231], v[94:95]
	v_mfma_f32_32x32x16_bf16 v[16:31], v[180:183], v[168:171], v[16:31]
	v_sub_f32_e32 v64, v64, v143
	v_sub_f32_e32 v65, v65, v143
	v_sub_f32_e32 v66, v66, v143
	v_sub_f32_e32 v67, v67, v143
	v_sub_f32_e32 v68, v68, v143
	v_sub_f32_e32 v69, v69, v143
	v_sub_f32_e32 v70, v70, v143
	v_sub_f32_e32 v71, v71, v143
	s_waitcnt lgkmcnt(1)
	v_mfma_f32_32x32x16_bf16 v[48:63], v[152:155], v[108:111], v[48:63]
	v_exp_f32_e32 v64, v64
	v_exp_f32_e32 v65, v65
	v_exp_f32_e32 v66, v66
	v_exp_f32_e32 v67, v67
	v_mfma_f32_32x32x16_bf16 v[0:15], v[184:187], v[80:83], v[0:15]
	v_exp_f32_e32 v68, v68
	v_exp_f32_e32 v69, v69
	v_exp_f32_e32 v70, v70
	v_exp_f32_e32 v71, v71
	v_mfma_f32_32x32x16_bf16 v[16:31], v[188:191], v[80:83], v[16:31]
	v_cvt_pk_bf16_f32 v168, v64, v65
	v_cvt_pk_bf16_f32 v169, v66, v67
	v_cvt_pk_bf16_f32 v170, v68, v69
	v_cvt_pk_bf16_f32 v171, v70, v71
	v_mfma_f32_32x32x16_bf16 v[32:47], v[226:229], v[108:111], v[32:47]
	v_pk_add_f32 v[230:231], v[230:231], v[64:65]
	v_pk_add_f32 v[230:231], v[230:231], v[66:67]
	v_pk_add_f32 v[230:231], v[230:231], v[68:69]
	v_pk_add_f32 v[230:231], v[230:231], v[70:71]
	v_mfma_f32_32x32x16_bf16 v[48:63], v[206:209], v[116:119], v[48:63]
	v_sub_f32_e32 v72, v72, v143
	v_sub_f32_e32 v73, v73, v143
	v_sub_f32_e32 v74, v74, v143
	v_sub_f32_e32 v75, v75, v143
	v_sub_f32_e32 v76, v76, v143
	v_sub_f32_e32 v77, v77, v143
	v_sub_f32_e32 v78, v78, v143
	v_sub_f32_e32 v79, v79, v143
	v_mfma_f32_32x32x16_bf16 v[32:47], v[236:239], v[116:119], v[32:47]
	s_andn2_b64 vcc, exec, s[10:11]
	s_cbranch_vccnz .Latt_wskip_o1
	s_waitcnt vmcnt(1)
	ds_write_b128 v162, v[120:123] offset:13312
	s_and_saveexec_b64 s[2:3], s[6:7]
	s_cbranch_execz .Latt_wk_o1
	s_waitcnt vmcnt(0)
	ds_write_b128 v164, v[124:127] offset:13440

; #define LAS __attribute__((address_space(3)))
; __device__ __forceinline__ unsigned pk_bf16(float lo, float hi) { unsigned r; asm("v_cvt_pk_bf16_f32 %0, %1, %2" : "=v"(r) : "v"(lo), "v"(hi)); return r; }
; __device__ __forceinline__ float fexp2(float x) { return __builtin_amdgcn_exp2f(x); }
; #define ATT_WRITEK(rk, rr, buf) do { LAS unsigned char* nb_ = lds + (buf) * KBUF; *(LAS u32x4*)(nb_ + skn) = rk; if (tid < 256) *(LAS u32x4*)(nb_ + skr) = rr; } while (0)
; #define ATT_WRITEV(rv, buf) do { LAS u32x2* p_ = (LAS u32x2*)(ldsv + (buf) * VBUF + svt); u32x2 lo_ = {rv[0], rv[1]}, hi_ = {rv[2], rv[3]}; p_[0] = lo_; p_[1] = hi_; } while (0)
; template <int MODE>
; __device__ __forceinline__ void attn_pv(const LAS unsigned char* vb_, f32x16 (&st)[2], f32x16 (&ot)[2], float& mrun, float& lsum, const int ql, const int hf, const int lane) {
;     ...
;     float ps = 0.f;
; #pragma unroll
;     for (int kb = 0; kb < 2; ++kb)
; #pragma unroll
;         for (int i = 0; i < 16; ++i) { const float p = fexp2(st[kb][i] - mrun); st[kb][i] = p; ps += p; }
;     lsum += ps;
;     } else lsum += st[0][0];
; #pragma unroll
;     for (int kb = 0; kb < 2; ++kb)
; #pragma unroll
;         for (int sI = 0; sI < 2; ++sI) {
;             u32x4 pw = {pk_bf16(st[kb][8 * sI + 0], st[kb][8 * sI + 1]), pk_bf16(st[kb][8 * sI + 2], st[kb][8 * sI + 3]),
;                         pk_bf16(st[kb][8 * sI + 4], st[kb][8 * sI + 5]), pk_bf16(st[kb][8 * sI + 6], st[kb][8 * sI + 7])};
;             const bf16x8 pf = __builtin_bit_cast(bf16x8, pw);
; #pragma unroll
;             for (int db = 0; db < 2; ++db) {
;                 const LAS unsigned char* vp = vb_ + (db * 32 + ql) * VROW + (kb * 32 + 16 * sI + 4 * hf) * 2;
;                 const u32x2 v0 = *(const LAS u32x2*)vp, v1 = *(const LAS u32x2*)(vp + 16);
;                 u32x4 vw = {v0[0], v0[1], v1[0], v1[1]};
;                 ot[db] = att_mma<MODE>(__builtin_bit_cast(bf16x8, vw), pf, ot[db]);
;             }
;         }
; }
; template <int MODE>
; __device__ __forceinline__ void attn_phase(const Args& a, bool do_ctx, LAS unsigned char* lds, const int wid_s) {
;     ...
;             attn_pv<MODE>(ldsv + VBUF, sb, ot, mrun, lsum, ql, hf, lane);
;             if (t + 3 < nkt) ATT_WRITEK(kK, kR, 1);
;             if (t + 2 < nkt) ATT_WRITEV(vV, 0);
.Latt_wskip_o1:
	s_waitcnt vmcnt(0)
	ds_write2_b64 v141, v[128:129], v[130:131] offset1:2
	v_exp_f32_e32 v72, v72
	v_exp_f32_e32 v73, v73
	v_exp_f32_e32 v74, v74
	v_exp_f32_e32 v75, v75
	v_mfma_f32_32x32x16_bf16 v[0:15], v[192:195], v[168:171], v[0:15]
	v_exp_f32_e32 v76, v76
	v_exp_f32_e32 v77, v77
	v_exp_f32_e32 v78, v78
	v_exp_f32_e32 v79, v79
	v_mfma_f32_32x32x16_bf16 v[16:31], v[196:199], v[168:171], v[16:31]
	v_cvt_pk_bf16_f32 v80, v72, v73
	v_cvt_pk_bf16_f32 v81, v74, v75
	v_cvt_pk_bf16_f32 v82, v76, v77
	v_cvt_pk_bf16_f32 v83, v78, v79
	v_pk_add_f32 v[230:231], v[230:231], v[72:73]
	v_pk_add_f32 v[230:231], v[230:231], v[74:75]
	v_pk_add_f32 v[230:231], v[230:231], v[76:77]
	v_pk_add_f32 v[230:231], v[230:231], v[78:79]
	v_add_f32_e32 v230, v230, v231
	v_add_f32_e32 v167, v167, v230
	s_waitcnt lgkmcnt(0)
	v_mfma_f32_32x32x16_bf16 v[0:15], v[172:175], v[80:83], v[0:15]
	v_mfma_f32_32x32x16_bf16 v[16:31], a[0:3], v[80:83], v[16:31]
	s_branch .LBB0_434
.Latt_o_tail:
	ds_read_b128 v[176:179], v240 offset:35840
	ds_read_b128 v[180:183], v240 offset:40448
	ds_read_b128 v[184:187], v240 offset:35872
	ds_read_b128 v[188:191], v240 offset:40480
	ds_read_b128 v[192:195], v240 offset:35904
	ds_read_b128 v[196:199], v240 offset:40512
	ds_read_b128 v[172:175], v240 offset:35936
	ds_read_b128 a[0:3], v240 offset:40544
	v_max3_f32 v156, v80, v64, v81
	v_max3_f32 v157, v65, v82, v66
	v_max3_f32 v156, v156, v83, v67
	v_max3_f32 v157, v157, v84, v68
	v_max3_f32 v156, v156, v85, v69
	v_max3_f32 v157, v157, v86, v70
	v_max3_f32 v156, v156, v87, v71
	v_max3_f32 v157, v157, v88, v72
	v_max3_f32 v156, v156, v89, v73
	v_max3_f32 v157, v157, v90, v74
	v_max3_f32 v156, v156, v91, v75
	v_max3_f32 v157, v157, v92, v76
	v_max3_f32 v156, v156, v93, v77
	v_max3_f32 v157, v157, v94, v78
	v_max3_f32 v156, v156, v95, v79
	v_max3_f32 v157, v156, v157, v157
	v_add_f32_e32 v156, 0x41000000, v143
	v_cmp_gt_f32_e32 vcc, v157, v156
	s_cbranch_vccnz .Latt_ot_nors_resc
.Latt_ot_nors:
	v_sub_f32_e32 v80, v80, v143
	v_sub_f32_e32 v81, v81, v143
	v_sub_f32_e32 v82, v82, v143
	v_sub_f32_e32 v83, v83, v143
	v_sub_f32_e32 v84, v84, v143
	v_sub_f32_e32 v85, v85, v143
	v_sub_f32_e32 v86, v86, v143
	v_sub_f32_e32 v87, v87, v143
	v_exp_f32_e32 v80, v80
	v_exp_f32_e32 v81, v81
	v_exp_f32_e32 v82, v82
	v_exp_f32_e32 v83, v83
	v_exp_f32_e32 v84, v84
	v_exp_f32_e32 v85, v85
	v_exp_f32_e32 v86, v86
	v_exp_f32_e32 v87, v87
	v_cvt_pk_bf16_f32 v168, v80, v81
	v_cvt_pk_bf16_f32 v169, v82, v83
	v_cvt_pk_bf16_f32 v170, v84, v85
	v_cvt_pk_bf16_f32 v171, v86, v87
	v_pk_add_f32 v[230:231], v[80:81], v[82:83]
	v_pk_add_f32 v[230:231], v[230:231], v[84:85]
	v_pk_add_f32 v[230:231], v[230:231], v[86:87]
	v_sub_f32_e32 v88, v88, v143
	v_sub_f32_e32 v89, v89, v143
	v_sub_f32_e32 v90, v90, v143
	v_sub_f32_e32 v91, v91, v143
	v_sub_f32_e32 v92, v92, v143
	v_sub_f32_e32 v93, v93, v143
	v_sub_f32_e32 v94, v94, v143
	v_sub_f32_e32 v95, v95, v143
	v_exp_f32_e32 v88, v88
	v_exp_f32_e32 v89, v89
	v_exp_f32_e32 v90, v90
	v_exp_f32_e32 v91, v91
	s_waitcnt lgkmcnt(0)
	v_mfma_f32_32x32x16_bf16 v[0:15], v[176:179], v[168:171], v[0:15]
	v_exp_f32_e32 v92, v92
	v_exp_f32_e32 v93, v93
	v_exp_f32_e32 v94, v94
	v_exp_f32_e32 v95, v95
	v_mfma_f32_32x32x16_bf16 v[16:31], v[180:183], v[168:171], v[16:31]
	v_cvt_pk_bf16_f32 v80, v88, v89
	v_cvt_pk_bf16_f32 v81, v90, v91
	v_cvt_pk_bf16_f32 v82, v92, v93
	v_cvt_pk_bf16_f32 v83, v94, v95
	v_pk_add_f32 v[230:231], v[230:231], v[88:89]
	v_pk_add_f32 v[230:231], v[230:231], v[90:91]
	v_pk_add_f32 v[230:231], v[230:231], v[92:93]
	v_pk_add_f32 v[230:231], v[230:231], v[94:95]
	v_sub_f32_e32 v64, v64, v143
	v_sub_f32_e32 v65, v65, v143
	v_sub_f32_e32 v66, v66, v143
	v_sub_f32_e32 v67, v67, v143
	v_sub_f32_e32 v68, v68, v143
	v_sub_f32_e32 v69, v69, v143
	v_sub_f32_e32 v70, v70, v143
	v_sub_f32_e32 v71, v71, v143
	v_mfma_f32_32x32x16_bf16 v[0:15], v[184:187], v[80:83], v[0:15]
	v_exp_f32_e32 v64, v64
	v_exp_f32_e32 v65, v65
	v_exp_f32_e32 v66, v66
	v_exp_f32_e32 v67, v67
	v_mfma_f32_32x32x16_bf16 v[16:31], v[188:191], v[80:83], v[16:31]
	v_exp_f32_e32 v68, v68
	v_exp_f32_e32 v69, v69
	v_exp_f32_e32 v70, v70
	v_exp_f32_e32 v71, v71
	v_cvt_pk_bf16_f32 v168, v64, v65
	v_cvt_pk_bf16_f32 v169, v66, v67
	v_cvt_pk_bf16_f32 v170, v68, v69
	v_cvt_pk_bf16_f32 v171, v70, v71
	v_pk_add_f32 v[230:231], v[230:231], v[64:65]
	v_pk_add_f32 v[230:231], v[230:231], v[66:67]
	v_pk_add_f32 v[230:231], v[230:231], v[68:69]
	v_pk_add_f32 v[230:231], v[230:231], v[70:71]
	v_sub_f32_e32 v72, v72, v143
	v_sub_f32_e32 v73, v73, v143
	v_sub_f32_e32 v74, v74, v143
	v_sub_f32_e32 v75, v75, v143
	v_sub_f32_e32 v76, v76, v143
	v_sub_f32_e32 v77, v77, v143
	v_sub_f32_e32 v78, v78, v143
	v_sub_f32_e32 v79, v79, v143
	v_mfma_f32_32x32x16_bf16 v[0:15], v[192:195], v[168:171], v[0:15]
	v_exp_f32_e32 v72, v72
	v_exp_f32_e32 v73, v73
	v_exp_f32_e32 v74, v74
	v_exp_f32_e32 v75, v75
	v_mfma_f32_32x32x16_bf16 v[16:31], v[196:199], v[168:171], v[16:31]
	v_exp_f32_e32 v76, v76
	v_exp_f32_e32 v77, v77
	v_exp_f32_e32 v78, v78
	v_exp_f32_e32 v79, v79
	v_cvt_pk_bf16_f32 v80, v72, v73
	v_cvt_pk_bf16_f32 v81, v74, v75
	v_cvt_pk_bf16_f32 v82, v76, v77
	v_cvt_pk_bf16_f32 v83, v78, v79
	v_pk_add_f32 v[230:231], v[230:231], v[72:73]
	v_pk_add_f32 v[230:231], v[230:231], v[74:75]
	v_pk_add_f32 v[230:231], v[230:231], v[76:77]
	v_pk_add_f32 v[230:231], v[230:231], v[78:79]
	v_add_f32_e32 v230, v230, v231
	v_add_f32_e32 v167, v167, v230
	v_mfma_f32_32x32x16_bf16 v[0:15], v[172:175], v[80:83], v[0:15]
	v_mfma_f32_32x32x16_bf16 v[16:31], a[0:3], v[80:83], v[16:31]
.Latt_o_end:
	s_andn2_b64 vcc, exec, s[10:11]
	s_cbranch_vccnz .LBB0_456
	s_waitcnt vmcnt(1)
	ds_write_b128 v162, v[120:123] offset:13312
	s_and_saveexec_b64 s[2:3], s[6:7]
	s_cbranch_execz .LBB0_455
	s_waitcnt vmcnt(0)
	ds_write_b128 v164, v[124:127] offset:13440

; #define LAS __attribute__((address_space(3)))
; __device__ __forceinline__ float fexp2(float x) { return __builtin_amdgcn_exp2f(x); }
; template <int MODE>
; __device__ __forceinline__ void attn_pv(const LAS unsigned char* vb_, f32x16 (&st)[2], f32x16 (&ot)[2], float& mrun, float& lsum, const int ql, const int hf, const int lane) {
;     if (MODE != 1) {
;     float mx = max3f(st[0][0], st[1][0], st[0][1]), my = max3f(st[1][1], st[0][2], st[1][2]);
; #pragma unroll
;     for (int i = 3; i < 15; i += 2) { mx = max3f(mx, st[0][i], st[1][i]); my = max3f(my, st[0][i + 1], st[1][i + 1]); }
;     mx = max3f(mx, st[0][15], st[1][15]); mx = max3f(mx, my, my);
;     if (__builtin_amdgcn_ballot_w64(mx > mrun + 8.0f) != 0ull) {
;         mx = fmaxf(mx, shx32(mx, lane));
;         const float mnew = (mx > mrun + 8.0f) ? mx : mrun;
;         const float alpha = fexp2(mrun - mnew);
;         mrun = mnew; lsum *= alpha;
; #pragma unroll
;         for (int i = 0; i < 16; ++i) { ot[0][i] *= alpha; ot[1][i] *= alpha; }
;     }
;     float ps = 0.f;
; #pragma unroll
;     for (int kb = 0; kb < 2; ++kb)
; #pragma unroll
;         for (int i = 0; i < 16; ++i) { const float p = fexp2(st[kb][i] - mrun); st[kb][i] = p; ps += p; }
;     lsum += ps;
;     } else lsum += st[0][0];
; #pragma unroll
;     for (int kb = 0; kb < 2; ++kb)
; #pragma unroll
;         for (int sI = 0; sI < 2; ++sI) {
;             u32x4 pw = {pk_bf16(st[kb][8 * sI + 0], st[kb][8 * sI + 1]), pk_bf16(st[kb][8 * sI + 2], st[kb][8 * sI + 3]),
;                         pk_bf16(st[kb][8 * sI + 4], st[kb][8 * sI + 5]), pk_bf16(st[kb][8 * sI + 6], st[kb][8 * sI + 7])};
;             const bf16x8 pf = __builtin_bit_cast(bf16x8, pw);
; #pragma unroll
;             for (int db = 0; db < 2; ++db) {
;                 const LAS unsigned char* vp = vb_ + (db * 32 + ql) * VROW + (kb * 32 + 16 * sI + 4 * hf) * 2;
;                 const u32x2 v0 = *(const LAS u32x2*)vp, v1 = *(const LAS u32x2*)(vp + 16);
;                 u32x4 vw = {v0[0], v0[1], v1[0], v1[1]};
;                 ot[db] = att_mma<MODE>(__builtin_bit_cast(bf16x8, vw), pf, ot[db]);
;             }
;         }
; }
; template <int MODE>
; __device__ __forceinline__ void attn_phase(const Args& a, bool do_ctx, LAS unsigned char* lds, const int wid_s) {
;     ...
;             if (t + 2 < nkt) ATT_WRITEK(kK, kR, 0);
;             ATT_WRITEV(vV, 1);
.LattB_e:
	ds_read_b128 v[64:67], v165 offset:13312
	ds_read_b128 v[168:171], v165 offset:13344
	ds_read_b128 v[68:71], v165 offset:19968
	ds_read_b128 v[172:175], v165 offset:20000
	ds_read_b128 v[176:179], v165 offset:13376
	ds_read_b128 v[180:183], v165 offset:13408
	ds_read_b128 v[184:187], v165 offset:20032
	ds_read_b128 v[188:191], v165 offset:20064
	ds_read_b128 v[206:209], v240 offset:31232
	ds_read_b128 v[210:213], v240 offset:26624
	ds_read_b128 v[214:217], v240 offset:31264
	ds_read_b128 v[218:221], v240 offset:26656
	ds_read_b128 v[222:225], v240 offset:31296
	ds_read_b128 v[226:229], v240 offset:26688
	ds_read_b128 v[236:239], v240 offset:26720
	v_max3_f32 v156, v48, v32, v49
	v_max3_f32 v157, v33, v50, v34
	v_max3_f32 v156, v156, v51, v35
	v_max3_f32 v157, v157, v52, v36
	v_max3_f32 v156, v156, v53, v37
	v_max3_f32 v157, v157, v54, v38
	v_max3_f32 v156, v156, v55, v39
	v_max3_f32 v157, v157, v56, v40
	v_max3_f32 v156, v156, v57, v41
	v_max3_f32 v157, v157, v58, v42
	v_max3_f32 v156, v156, v59, v43
	v_max3_f32 v157, v157, v60, v44
	v_max3_f32 v156, v156, v61, v45
	v_max3_f32 v157, v157, v62, v46
	v_max3_f32 v156, v156, v63, v47
	v_max3_f32 v157, v156, v157, v157
	v_add_f32_e32 v156, 0x41000000, v143
	v_cmp_gt_f32_e32 vcc, v157, v156
	s_cbranch_vccnz .Latt_eB_nors_resc
.Latt_eB_nors:
	v_sub_f32_e32 v48, v48, v143
	v_sub_f32_e32 v49, v49, v143
	v_sub_f32_e32 v50, v50, v143
	v_sub_f32_e32 v51, v51, v143
	v_sub_f32_e32 v52, v52, v143
	v_sub_f32_e32 v53, v53, v143
	v_sub_f32_e32 v54, v54, v143
	v_sub_f32_e32 v55, v55, v143
	v_exp_f32_e32 v48, v48
	v_exp_f32_e32 v49, v49
	v_exp_f32_e32 v50, v50
	v_exp_f32_e32 v51, v51
	v_exp_f32_e32 v52, v52
	v_exp_f32_e32 v53, v53
	v_exp_f32_e32 v54, v54
	v_exp_f32_e32 v55, v55
	s_waitcnt lgkmcnt(11)
	v_mfma_f32_32x32x16_bf16 v[80:95], v[64:67], v[112:115], 0
	v_cvt_pk_bf16_f32 v152, v48, v49
	v_cvt_pk_bf16_f32 v153, v50, v51
	v_cvt_pk_bf16_f32 v154, v52, v53
	v_cvt_pk_bf16_f32 v155, v54, v55
	v_mfma_f32_32x32x16_bf16 v[64:79], v[68:71], v[112:115], 0
	v_pk_add_f32 v[230:231], v[48:49], v[50:51]
	v_pk_add_f32 v[230:231], v[230:231], v[52:53]
	v_pk_add_f32 v[230:231], v[230:231], v[54:55]
	v_mfma_f32_32x32x16_bf16 v[80:95], v[168:171], v[96:99], v[80:95]
	v_sub_f32_e32 v56, v56, v143
	v_sub_f32_e32 v57, v57, v143
	v_sub_f32_e32 v58, v58, v143
	v_sub_f32_e32 v59, v59, v143
	v_sub_f32_e32 v60, v60, v143
	v_sub_f32_e32 v61, v61, v143
	v_sub_f32_e32 v62, v62, v143
	v_sub_f32_e32 v63, v63, v143
	v_mfma_f32_32x32x16_bf16 v[64:79], v[172:175], v[96:99], v[64:79]
	ds_read_b128 v[168:171], v165 offset:13440
	ds_read_b128 v[172:175], v165 offset:13472
	ds_read_b128 v[192:195], v165 offset:20096
	ds_read_b128 v[196:199], v165 offset:20128
	v_exp_f32_e32 v56, v56
	v_exp_f32_e32 v57, v57
	v_exp_f32_e32 v58, v58
	v_exp_f32_e32 v59, v59
	s_waitcnt lgkmcnt(11)
	v_mfma_f32_32x32x16_bf16 v[80:95], v[176:179], v[100:103], v[80:95]
	ds_read_b128 a[0:3], v240 offset:31328
	v_exp_f32_e32 v60, v60
	v_exp_f32_e32 v61, v61
	v_exp_f32_e32 v62, v62
	v_exp_f32_e32 v63, v63
	v_mfma_f32_32x32x16_bf16 v[64:79], v[184:187], v[100:103], v[64:79]
	v_mfma_f32_32x32x16_bf16 v[80:95], v[180:183], v[104:107], v[80:95]
	v_cvt_pk_bf16_f32 v48, v56, v57
	v_cvt_pk_bf16_f32 v49, v58, v59
	v_cvt_pk_bf16_f32 v50, v60, v61
	v_cvt_pk_bf16_f32 v51, v62, v63
	v_mfma_f32_32x32x16_bf16 v[64:79], v[188:191], v[104:107], v[64:79]
	s_waitcnt lgkmcnt(10)
	v_mfma_f32_32x32x16_bf16 v[16:31], v[206:209], v[152:155], v[16:31]
	v_pk_add_f32 v[230:231], v[230:231], v[56:57]
	v_pk_add_f32 v[230:231], v[230:231], v[58:59]
	v_pk_add_f32 v[230:231], v[230:231], v[60:61]
	v_pk_add_f32 v[230:231], v[230:231], v[62:63]
	v_mfma_f32_32x32x16_bf16 v[0:15], v[210:213], v[152:155], v[0:15]
	s_andn2_b64 vcc, exec, s[10:11]
	s_cbranch_vccnz .Latt_wskip_eB1
	s_waitcnt vmcnt(2)
	ds_write_b128 v162, v[120:123]
	s_and_saveexec_b64 s[2:3], s[6:7]
	s_cbranch_execz .Latt_wk_eB1
	s_waitcnt vmcnt(1)
	ds_write_b128 v164, v[124:127] offset:128

; #define LAS __attribute__((address_space(3)))
; __device__ __forceinline__ unsigned pk_bf16(float lo, float hi) { unsigned r; asm("v_cvt_pk_bf16_f32 %0, %1, %2" : "=v"(r) : "v"(lo), "v"(hi)); return r; }
; __device__ __forceinline__ float fexp2(float x) { return __builtin_amdgcn_exp2f(x); }
; #define ATT_LOADK(rk, rr, kt_) do { if (MODE == 3 && (kt_) > 1) break; rk = *(const u32x4*)(gkn + (size_t)(kt_) * 64 * 512); rr = *(const u32x4*)(gkr + (size_t)(kt_) * 64 * 32); } while (0)
; template <int MODE>
; __device__ __forceinline__ void attn_pv(const LAS unsigned char* vb_, f32x16 (&st)[2], f32x16 (&ot)[2], float& mrun, float& lsum, const int ql, const int hf, const int lane) {
;     ...
;     float ps = 0.f;
; #pragma unroll
;     for (int kb = 0; kb < 2; ++kb)
; #pragma unroll
;         for (int i = 0; i < 16; ++i) { const float p = fexp2(st[kb][i] - mrun); st[kb][i] = p; ps += p; }
;     lsum += ps;
;     } else lsum += st[0][0];
; #pragma unroll
;     for (int kb = 0; kb < 2; ++kb)
; #pragma unroll
;         for (int sI = 0; sI < 2; ++sI) {
;             u32x4 pw = {pk_bf16(st[kb][8 * sI + 0], st[kb][8 * sI + 1]), pk_bf16(st[kb][8 * sI + 2], st[kb][8 * sI + 3]),
;                         pk_bf16(st[kb][8 * sI + 4], st[kb][8 * sI + 5]), pk_bf16(st[kb][8 * sI + 6], st[kb][8 * sI + 7])};
;             const bf16x8 pf = __builtin_bit_cast(bf16x8, pw);
; #pragma unroll
;             for (int db = 0; db < 2; ++db) {
;                 const LAS unsigned char* vp = vb_ + (db * 32 + ql) * VROW + (kb * 32 + 16 * sI + 4 * hf) * 2;
;                 const u32x2 v0 = *(const LAS u32x2*)vp, v1 = *(const LAS u32x2*)(vp + 16);
;                 u32x4 vw = {v0[0], v0[1], v1[0], v1[1]};
;                 ot[db] = att_mma<MODE>(__builtin_bit_cast(bf16x8, vw), pf, ot[db]);
;             }
;         }
; }
; template <int MODE>
; __device__ __forceinline__ void attn_phase(const Args& a, bool do_ctx, LAS unsigned char* lds, const int wid_s) {
;     ...
;             __syncthreads();
;             if (t + 3 < nkt) ATT_LOADK(kK, kR, t + 3);
;             if (t + 2 < nkt) ATT_LOADV(vV, t + 2);
;             if (t + 2 < nkt) attn_qk<MODE>(lds, qf, sa, ql, hf);
;             __builtin_amdgcn_sched_barrier(0);
;             attn_pv<MODE>(ldsv + VBUF, sb, ot, mrun, lsum, ql, hf, lane);
.Latt_wskip_eB1:
	s_waitcnt vmcnt(0)
	ds_write2_b64 v251, v[128:129], v[130:131] offset1:2
	v_sub_f32_e32 v32, v32, v143
	v_sub_f32_e32 v33, v33, v143
	v_sub_f32_e32 v34, v34, v143
	v_sub_f32_e32 v35, v35, v143
	v_sub_f32_e32 v36, v36, v143
	v_sub_f32_e32 v37, v37, v143
	v_sub_f32_e32 v38, v38, v143
	v_sub_f32_e32 v39, v39, v143
	v_exp_f32_e32 v32, v32
	v_exp_f32_e32 v33, v33
	v_exp_f32_e32 v34, v34
	v_exp_f32_e32 v35, v35
	s_waitcnt lgkmcnt(0)
	s_barrier
	v_mfma_f32_32x32x16_bf16 v[80:95], v[168:171], v[108:111], v[80:95]
	v_exp_f32_e32 v36, v36
	v_exp_f32_e32 v37, v37
	v_exp_f32_e32 v38, v38
	v_exp_f32_e32 v39, v39
	v_mfma_f32_32x32x16_bf16 v[16:31], v[214:217], v[48:51], v[16:31]
	v_mfma_f32_32x32x16_bf16 v[0:15], v[218:221], v[48:51], v[0:15]
	v_cvt_pk_bf16_f32 v152, v32, v33
	v_cvt_pk_bf16_f32 v153, v34, v35
	v_cvt_pk_bf16_f32 v154, v36, v37
	v_cvt_pk_bf16_f32 v155, v38, v39
	v_mfma_f32_32x32x16_bf16 v[64:79], v[192:195], v[108:111], v[64:79]
	v_pk_add_f32 v[230:231], v[230:231], v[32:33]
	v_pk_add_f32 v[230:231], v[230:231], v[34:35]
	v_pk_add_f32 v[230:231], v[230:231], v[36:37]
	v_pk_add_f32 v[230:231], v[230:231], v[38:39]
	v_mfma_f32_32x32x16_bf16 v[80:95], v[172:175], v[116:119], v[80:95]
	v_sub_f32_e32 v40, v40, v143
	v_sub_f32_e32 v41, v41, v143
	v_sub_f32_e32 v42, v42, v143
	v_sub_f32_e32 v43, v43, v143
	v_sub_f32_e32 v44, v44, v143
	v_sub_f32_e32 v45, v45, v143
	v_sub_f32_e32 v46, v46, v143
	v_sub_f32_e32 v47, v47, v143
	v_mfma_f32_32x32x16_bf16 v[64:79], v[196:199], v[116:119], v[64:79]
	v_exp_f32_e32 v40, v40
	v_exp_f32_e32 v41, v41
	v_exp_f32_e32 v42, v42
	v_exp_f32_e32 v43, v43
	v_mfma_f32_32x32x16_bf16 v[16:31], v[222:225], v[152:155], v[16:31]
	v_exp_f32_e32 v44, v44
	v_exp_f32_e32 v45, v45
	v_exp_f32_e32 v46, v46
	v_exp_f32_e32 v47, v47
	v_mfma_f32_32x32x16_bf16 v[0:15], v[226:229], v[152:155], v[0:15]
	v_cvt_pk_bf16_f32 v48, v40, v41
	v_cvt_pk_bf16_f32 v49, v42, v43
	v_cvt_pk_bf16_f32 v50, v44, v45
	v_cvt_pk_bf16_f32 v51, v46, v47
	v_pk_add_f32 v[230:231], v[230:231], v[40:41]
	v_pk_add_f32 v[230:231], v[230:231], v[42:43]
	v_pk_add_f32 v[230:231], v[230:231], v[44:45]
	v_pk_add_f32 v[230:231], v[230:231], v[46:47]
	v_add_f32_e32 v230, v230, v231
	v_add_f32_e32 v167, v167, v230
	v_mfma_f32_32x32x16_bf16 v[0:15], v[236:239], v[48:51], v[0:15]
	v_mfma_f32_32x32x16_bf16 v[16:31], a[0:3], v[48:51], v[16:31]
	s_not_b64 s[8:9], s[10:11]
	s_cmp_lt_u32 s12, s25
	s_cselect_b64 s[10:11], -1, 0
	s_cmp_ge_u32 s12, s25
	s_branch .Latt_otop
.LattB_o:
	ds_read_b128 v[32:35], v165
	ds_read_b128 v[152:155], v165 offset:32
	ds_read_b128 v[36:39], v165 offset:6656
	ds_read_b128 v[206:209], v165 offset:6688
	ds_read_b128 v[210:213], v165 offset:64
	ds_read_b128 v[214:217], v165 offset:96
	ds_read_b128 v[218:221], v165 offset:6720
	ds_read_b128 v[222:225], v165 offset:6752
	ds_read_b128 v[176:179], v240 offset:35840
	ds_read_b128 v[180:183], v240 offset:40448
	ds_read_b128 v[184:187], v240 offset:35872
	ds_read_b128 v[188:191], v240 offset:40480
	ds_read_b128 v[192:195], v240 offset:35904
	ds_read_b128 v[196:199], v240 offset:40512
	ds_read_b128 v[172:175], v240 offset:35936
	v_max3_f32 v156, v80, v64, v81
	v_max3_f32 v157, v65, v82, v66
	v_max3_f32 v156, v156, v83, v67
	v_max3_f32 v157, v157, v84, v68
	v_max3_f32 v156, v156, v85, v69
	v_max3_f32 v157, v157, v86, v70
	v_max3_f32 v156, v156, v87, v71
	v_max3_f32 v157, v157, v88, v72
	v_max3_f32 v156, v156, v89, v73
	v_max3_f32 v157, v157, v90, v74
	v_max3_f32 v156, v156, v91, v75
	v_max3_f32 v157, v157, v92, v76
	v_max3_f32 v156, v156, v93, v77
	v_max3_f32 v157, v157, v94, v78
	v_max3_f32 v156, v156, v95, v79
	v_max3_f32 v157, v156, v157, v157
	v_add_f32_e32 v156, 0x41000000, v143
	v_cmp_gt_f32_e32 vcc, v157, v156
	s_cbranch_vccnz .Latt_oB_nors_resc
.Latt_oB_nors:
	v_sub_f32_e32 v80, v80, v143
	v_sub_f32_e32 v81, v81, v143
	v_sub_f32_e32 v82, v82, v143
	v_sub_f32_e32 v83, v83, v143
	v_sub_f32_e32 v84, v84, v143
	v_sub_f32_e32 v85, v85, v143
	v_sub_f32_e32 v86, v86, v143
	v_sub_f32_e32 v87, v87, v143
	v_exp_f32_e32 v80, v80
	v_exp_f32_e32 v81, v81
	v_exp_f32_e32 v82, v82
	v_exp_f32_e32 v83, v83
	v_exp_f32_e32 v84, v84
	v_exp_f32_e32 v85, v85
	v_exp_f32_e32 v86, v86
	v_exp_f32_e32 v87, v87
	s_waitcnt lgkmcnt(11)
	v_mfma_f32_32x32x16_bf16 v[48:63], v[32:35], v[112:115], 0
	v_cvt_pk_bf16_f32 v168, v80, v81
	v_cvt_pk_bf16_f32 v169, v82, v83
	v_cvt_pk_bf16_f32 v170, v84, v85
	v_cvt_pk_bf16_f32 v171, v86, v87
	v_mfma_f32_32x32x16_bf16 v[32:47], v[36:39], v[112:115], 0
	v_pk_add_f32 v[230:231], v[80:81], v[82:83]
	v_pk_add_f32 v[230:231], v[230:231], v[84:85]
	v_pk_add_f32 v[230:231], v[230:231], v[86:87]
	v_mfma_f32_32x32x16_bf16 v[48:63], v[152:155], v[96:99], v[48:63]
	v_sub_f32_e32 v88, v88, v143
	v_sub_f32_e32 v89, v89, v143
	v_sub_f32_e32 v90, v90, v143
	v_sub_f32_e32 v91, v91, v143
	v_sub_f32_e32 v92, v92, v143
	v_sub_f32_e32 v93, v93, v143
	v_sub_f32_e32 v94, v94, v143
	v_sub_f32_e32 v95, v95, v143
	v_mfma_f32_32x32x16_bf16 v[32:47], v[206:209], v[96:99], v[32:47]
	ds_read_b128 v[152:155], v165 offset:128
	ds_read_b128 v[206:209], v165 offset:160
	ds_read_b128 v[226:229], v165 offset:6784
	ds_read_b128 v[236:239], v165 offset:6816
	v_exp_f32_e32 v88, v88
	v_exp_f32_e32 v89, v89
	v_exp_f32_e32 v90, v90
	v_exp_f32_e32 v91, v91
	s_waitcnt lgkmcnt(11)
	v_mfma_f32_32x32x16_bf16 v[48:63], v[210:213], v[100:103], v[48:63]
	ds_read_b128 a[0:3], v240 offset:40544
	v_exp_f32_e32 v92, v92
	v_exp_f32_e32 v93, v93
	v_exp_f32_e32 v94, v94
	v_exp_f32_e32 v95, v95
	v_mfma_f32_32x32x16_bf16 v[32:47], v[218:221], v[100:103], v[32:47]
	v_mfma_f32_32x32x16_bf16 v[48:63], v[214:217], v[104:107], v[48:63]
	v_cvt_pk_bf16_f32 v80, v88, v89
	v_cvt_pk_bf16_f32 v81, v90, v91
	v_cvt_pk_bf16_f32 v82, v92, v93
	v_cvt_pk_bf16_f32 v83, v94, v95
	v_mfma_f32_32x32x16_bf16 v[32:47], v[222:225], v[104:107], v[32:47]
	s_waitcnt lgkmcnt(10)
	v_mfma_f32_32x32x16_bf16 v[0:15], v[176:179], v[168:171], v[0:15]
	v_pk_add_f32 v[230:231], v[230:231], v[88:89]
	v_pk_add_f32 v[230:231], v[230:231], v[90:91]
	v_pk_add_f32 v[230:231], v[230:231], v[92:93]
	v_pk_add_f32 v[230:231], v[230:231], v[94:95]
	v_mfma_f32_32x32x16_bf16 v[16:31], v[180:183], v[168:171], v[16:31]
	s_andn2_b64 vcc, exec, s[10:11]
	s_cbranch_vccnz .Latt_wskip_oB1
	s_waitcnt vmcnt(1)
	ds_write_b128 v162, v[120:123] offset:13312
	s_and_saveexec_b64 s[2:3], s[6:7]
	s_cbranch_execz .Latt_wk_oB1
	s_waitcnt vmcnt(0)
	ds_write_b128 v164, v[124:127] offset:13440

; #define LAS __attribute__((address_space(3)))
; __device__ __forceinline__ float shx32(float v, int lane) { return __int_as_float(__builtin_amdgcn_ds_bpermute((lane ^ 32) << 2, __float_as_int(v))); }
; __device__ __forceinline__ unsigned pk_bf16(float lo, float hi) { unsigned r; asm("v_cvt_pk_bf16_f32 %0, %1, %2" : "=v"(r) : "v"(lo), "v"(hi)); return r; }
; __device__ __forceinline__ float fexp2(float x) { return __builtin_amdgcn_exp2f(x); }
; template <int MODE>
; __device__ __forceinline__ void attn_pv(const LAS unsigned char* vb_, f32x16 (&st)[2], f32x16 (&ot)[2], float& mrun, float& lsum, const int ql, const int hf, const int lane) {
;     ...
;     if (__builtin_amdgcn_ballot_w64(mx > mrun + 8.0f) != 0ull) {
;         mx = fmaxf(mx, shx32(mx, lane));
;         const float mnew = (mx > mrun + 8.0f) ? mx : mrun;
;         const float alpha = fexp2(mrun - mnew);
;         mrun = mnew; lsum *= alpha;
; #pragma unroll
;         for (int i = 0; i < 16; ++i) { ot[0][i] *= alpha; ot[1][i] *= alpha; }
;     }
;     float ps = 0.f;
; #pragma unroll
;     for (int kb = 0; kb < 2; ++kb)
; #pragma unroll
;         for (int i = 0; i < 16; ++i) { const float p = fexp2(st[kb][i] - mrun); st[kb][i] = p; ps += p; }
;     lsum += ps;
;     } else lsum += st[0][0];
; #pragma unroll
;     for (int kb = 0; kb < 2; ++kb)
; #pragma unroll
;         for (int sI = 0; sI < 2; ++sI) {
;             u32x4 pw = {pk_bf16(st[kb][8 * sI + 0], st[kb][8 * sI + 1]), pk_bf16(st[kb][8 * sI + 2], st[kb][8 * sI + 3]),
;                         pk_bf16(st[kb][8 * sI + 4], st[kb][8 * sI + 5]), pk_bf16(st[kb][8 * sI + 6], st[kb][8 * sI + 7])};
;             const bf16x8 pf = __builtin_bit_cast(bf16x8, pw);
; #pragma unroll
;             for (int db = 0; db < 2; ++db) {
;                 const LAS unsigned char* vp = vb_ + (db * 32 + ql) * VROW + (kb * 32 + 16 * sI + 4 * hf) * 2;
;                 const u32x2 v0 = *(const LAS u32x2*)vp, v1 = *(const LAS u32x2*)(vp + 16);
;                 u32x4 vw = {v0[0], v0[1], v1[0], v1[1]};
;                 ot[db] = att_mma<MODE>(__builtin_bit_cast(bf16x8, vw), pf, ot[db]);
;             }
;         }
; }
.Latt_wskip_oB1:
	s_waitcnt vmcnt(0)
	ds_write2_b64 v141, v[128:129], v[130:131] offset1:2
	v_sub_f32_e32 v64, v64, v143
	v_sub_f32_e32 v65, v65, v143
	v_sub_f32_e32 v66, v66, v143
	v_sub_f32_e32 v67, v67, v143
	v_sub_f32_e32 v68, v68, v143
	v_sub_f32_e32 v69, v69, v143
	v_sub_f32_e32 v70, v70, v143
	v_sub_f32_e32 v71, v71, v143
	v_exp_f32_e32 v64, v64
	v_exp_f32_e32 v65, v65
	v_exp_f32_e32 v66, v66
	v_exp_f32_e32 v67, v67
	s_waitcnt lgkmcnt(0)
	s_barrier
	v_mfma_f32_32x32x16_bf16 v[48:63], v[152:155], v[108:111], v[48:63]
	v_exp_f32_e32 v68, v68
	v_exp_f32_e32 v69, v69
	v_exp_f32_e32 v70, v70
	v_exp_f32_e32 v71, v71
	v_mfma_f32_32x32x16_bf16 v[0:15], v[184:187], v[80:83], v[0:15]
	v_mfma_f32_32x32x16_bf16 v[16:31], v[188:191], v[80:83], v[16:31]
	v_cvt_pk_bf16_f32 v168, v64, v65
	v_cvt_pk_bf16_f32 v169, v66, v67
	v_cvt_pk_bf16_f32 v170, v68, v69
	v_cvt_pk_bf16_f32 v171, v70, v71
	v_mfma_f32_32x32x16_bf16 v[32:47], v[226:229], v[108:111], v[32:47]
	v_pk_add_f32 v[230:231], v[230:231], v[64:65]
	v_pk_add_f32 v[230:231], v[230:231], v[66:67]
	v_pk_add_f32 v[230:231], v[230:231], v[68:69]
	v_pk_add_f32 v[230:231], v[230:231], v[70:71]
	v_mfma_f32_32x32x16_bf16 v[48:63], v[206:209], v[116:119], v[48:63]
	v_sub_f32_e32 v72, v72, v143
	v_sub_f32_e32 v73, v73, v143
	v_sub_f32_e32 v74, v74, v143
	v_sub_f32_e32 v75, v75, v143
	v_sub_f32_e32 v76, v76, v143
	v_sub_f32_e32 v77, v77, v143
	v_sub_f32_e32 v78, v78, v143
	v_sub_f32_e32 v79, v79, v143
	v_mfma_f32_32x32x16_bf16 v[32:47], v[236:239], v[116:119], v[32:47]
	v_exp_f32_e32 v72, v72
	v_exp_f32_e32 v73, v73
	v_exp_f32_e32 v74, v74
	v_exp_f32_e32 v75, v75
	v_mfma_f32_32x32x16_bf16 v[0:15], v[192:195], v[168:171], v[0:15]
	v_exp_f32_e32 v76, v76
	v_exp_f32_e32 v77, v77
	v_exp_f32_e32 v78, v78
	v_exp_f32_e32 v79, v79
	v_mfma_f32_32x32x16_bf16 v[16:31], v[196:199], v[168:171], v[16:31]
	v_cvt_pk_bf16_f32 v80, v72, v73
	v_cvt_pk_bf16_f32 v81, v74, v75
	v_cvt_pk_bf16_f32 v82, v76, v77
	v_cvt_pk_bf16_f32 v83, v78, v79
	v_pk_add_f32 v[230:231], v[230:231], v[72:73]
	v_pk_add_f32 v[230:231], v[230:231], v[74:75]
	v_pk_add_f32 v[230:231], v[230:231], v[76:77]
	v_pk_add_f32 v[230:231], v[230:231], v[78:79]
	v_add_f32_e32 v230, v230, v231
	v_add_f32_e32 v167, v167, v230
	v_mfma_f32_32x32x16_bf16 v[0:15], v[172:175], v[80:83], v[0:15]
	v_mfma_f32_32x32x16_bf16 v[16:31], a[0:3], v[80:83], v[16:31]
	s_add_u32 s80, s80, 0x20000
	s_addc_u32 s81, s81, 0
	s_add_u32 s82, s82, 0x2000
	s_addc_u32 s83, s83, 0
	s_add_u32 s84, s84, 0x100
	s_addc_u32 s85, s85, 0
	s_add_i32 s12, s12, 2
	s_branch .LBB0_435
.Latt_e_nors_resc:
	ds_bpermute_b32 v231, v163, v157
	v_max_f32_e32 v157, v157, v157
	s_waitcnt lgkmcnt(0)
	v_max_f32_e32 v231, v231, v231
	v_max_f32_e32 v157, v157, v231
	v_cmp_gt_f32_e32 vcc, v157, v156
	s_nop 1
	v_cndmask_b32_e32 v157, v143, v157, vcc
	v_sub_f32_e32 v143, v143, v157
	v_exp_f32_e32 v156, v143
	v_mov_b32_e32 v143, v157
	v_mul_f32_e32 v167, v167, v156
	v_pk_mul_f32 v[14:15], v[14:15], v[156:157] op_sel_hi:[1,0]
	v_pk_mul_f32 v[12:13], v[12:13], v[156:157] op_sel_hi:[1,0]
	v_pk_mul_f32 v[10:11], v[10:11], v[156:157] op_sel_hi:[1,0]
	v_pk_mul_f32 v[8:9], v[8:9], v[156:157] op_sel_hi:[1,0]
	v_pk_mul_f32 v[6:7], v[6:7], v[156:157] op_sel_hi:[1,0]
	v_pk_mul_f32 v[4:5], v[4:5], v[156:157] op_sel_hi:[1,0]
	v_pk_mul_f32 v[2:3], v[2:3], v[156:157] op_sel_hi:[1,0]
	v_pk_mul_f32 v[0:1], v[0:1], v[156:157] op_sel_hi:[1,0]
	v_pk_mul_f32 v[30:31], v[30:31], v[156:157] op_sel_hi:[1,0]
	v_pk_mul_f32 v[28:29], v[28:29], v[156:157] op_sel_hi:[1,0]
	v_pk_mul_f32 v[26:27], v[26:27], v[156:157] op_sel_hi:[1,0]
	v_pk_mul_f32 v[24:25], v[24:25], v[156:157] op_sel_hi:[1,0]
	v_pk_mul_f32 v[22:23], v[22:23], v[156:157] op_sel_hi:[1,0]
	v_pk_mul_f32 v[20:21], v[20:21], v[156:157] op_sel_hi:[1,0]
	v_pk_mul_f32 v[18:19], v[18:19], v[156:157] op_sel_hi:[1,0]
	v_pk_mul_f32 v[16:17], v[16:17], v[156:157] op_sel_hi:[1,0]
	s_branch .Latt_e_nors
